# scan chunk start: first-step LDS operand reads issued before the per-chunk lane/mask setup and stagger (from v33)
# baseline (speedup 1.0000x reference)
; #define SC_GET(X, t) do { const float* p = rec + (t) * 320; w##X = *(const f32x4*)p; a##X = *(const f32x4*)(p + 4); b##X = *(const f32x4*)(p + 8); k##X = *(const f32x4*)(p + 12); q##X = *(const f32x4*)(p + 16); \
;                 v##X = *(const f32x4*)(VVa + (t) * 64); } while (0)
; DI void scan_phase(unsigned char* lds, const Ctx& a, const Op& d, const int variant) {
;     ...
;             } else if (!(variant & 1)) {
;                 const float* base = (const float*)(lds + bi * SC_BUF);
;                 const float* rec = base + jg * 20; const float* VVa = base + 10240 + rA * 2;
;                 f32x4 wA, aA, bA, kA, qA, vA, wB, aB, bB, kB, qB, vB;
;     ...
;                 SC_GET(A, 0);
.LBB0_453:
	s_and_b32 s48, s47, 1
	s_and_saveexec_b64 s[10:11], s[8:9]
	s_xor_b64 s[10:11], exec, s[10:11]
	s_cbranch_execz .LBB0_466
	s_mul_i32 s30, s48, 0xd000
	v_add_u32_e32 v175, s30, v157
	v_add_u32_e32 v123, s30, v158
	ds_read_b128 v[40:43], v175
	ds_read_b128 v[44:47], v175 offset:16
	ds_read_b128 v[48:51], v175 offset:32
	ds_read_b128 v[52:55], v175 offset:48
	ds_read_b128 v[56:59], v175 offset:64
	ds_read_b128 v[60:63], v123 offset:40960
	v_mbcnt_lo_u32_b32 v176, -1, 0
	v_mbcnt_hi_u32_b32 v176, -1, v176
	v_and_b32_e32 v179, 3, v176
	v_bfe_u32 v177, v176, 3, 1
	v_bfe_u32 v176, v176, 2, 1
	v_lshlrev_b32_e32 v177, 7, v177
	v_lshl_add_u32 v176, v176, 2, v177
	v_add3_u32 v178, v169, s30, v176
	v_mov_b32_e32 v151, 0xff0000
	v_cmp_eq_u32_e32 vcc, 0, v179
	s_nop 1
	v_cndmask_b32_e32 v178, v151, v178, vcc
	v_cndmask_b32_e64 v176, 0, 1.0, s[4:5]
	v_mov_b32_e32 v177, v176
	s_mov_b32 s34, 0x11111111
	s_mov_b32 s35, 0x11111111
	v_readfirstlane_b32 s39, v158
	s_nop 3
	s_lshr_b32 s39, s39, 6
	s_cmp_eq_u32 s39, 0
	s_cbranch_scc1 .Lscan_stag_done
